# GEMM K-loop: stage DMAs spread through the first MFMA group, M0 formed on SALU
# speedup vs baseline: 1.0058x; 1.0058x over previous
.LBB0_246:
	s_add_i32 s10, s7, 0xffffa000
	s_cmp_lg_u32 s7, 0
	s_cselect_b32 s12, s10, 0xc000
	v_add_u32_e32 v131, s7, v150
	s_waitcnt vmcnt(6)
	s_barrier
	v_add_u32_e32 v133, s7, v149
	ds_read_b128 v[154:157], v131 offset:0
	ds_read_b128 v[158:161], v131 offset:0x400
	ds_read_b128 v[162:165], v131 offset:0x800
	ds_read_b128 v[166:169], v131 offset:0xc00
	v_add_u32_e32 v131, s12, v147
	ds_read_b128 v[170:173], v133 offset:0
	ds_read_b128 v[174:177], v133 offset:0x400
	ds_read_b128 v[178:181], v133 offset:0x800
	ds_read_b128 v[200:203], v133 offset:0xc00
	ds_read_b128 v[204:207], v133 offset:0x1000
	ds_read_b128 v[208:211], v133 offset:0x1400
	ds_read_b128 v[212:215], v133 offset:0x1800
	ds_read_b128 v[216:219], v133 offset:0x1c00
	s_add_u32 s10, s8, s50
	s_addc_u32 s11, s9, s51
	v_readfirstlane_b32 s13, v131
	s_add_u32 s64, s5, s100
	s_addc_u32 s65, s6, 0
	s_sub_i32 s68, s13, s12
	s_lshr_b32 s68, s68, 1
	s_add_i32 s68, s68, s12
	s_addk_i32 s68, 0x4000
	s_mov_b32 m0, s13
	s_nop 0
	global_load_lds_dwordx4 v0, s[10:11]
	s_add_u32 m0, s13, 0x400
	s_nop 0
	global_load_lds_dwordx4 v130, s[10:11]
	s_waitcnt lgkmcnt(4)
	s_nop 0
	v_mfma_f32_16x16x32_bf16 v[126:129], v[154:157], v[170:173], v[126:129]
	v_mfma_f32_16x16x32_bf16 v[122:125], v[154:157], v[174:177], v[122:125]
	v_mfma_f32_16x16x32_bf16 v[118:121], v[154:157], v[178:181], v[118:121]
	v_mfma_f32_16x16x32_bf16 v[114:117], v[154:157], v[200:203], v[114:117]
	s_add_u32 m0, s13, 0x800
	s_nop 0
	global_load_lds_dwordx4 v132, s[10:11]
	v_mfma_f32_16x16x32_bf16 v[110:113], v[158:161], v[170:173], v[110:113]
	v_mfma_f32_16x16x32_bf16 v[102:105], v[158:161], v[174:177], v[102:105]
	v_mfma_f32_16x16x32_bf16 v[94:97], v[158:161], v[178:181], v[94:97]
	v_mfma_f32_16x16x32_bf16 v[86:89], v[158:161], v[200:203], v[86:89]
	s_add_u32 m0, s13, 0xc00
	s_nop 0
	global_load_lds_dwordx4 v136, s[10:11]
	v_mfma_f32_16x16x32_bf16 v[78:81], v[162:165], v[170:173], v[78:81]
	v_mfma_f32_16x16x32_bf16 v[70:73], v[162:165], v[174:177], v[70:73]
	v_mfma_f32_16x16x32_bf16 v[62:65], v[162:165], v[178:181], v[62:65]
	v_mfma_f32_16x16x32_bf16 v[54:57], v[162:165], v[200:203], v[54:57]
	s_mov_b32 m0, s68
	s_nop 0
	global_load_lds_dwordx4 v138, s[64:65]
	v_mfma_f32_16x16x32_bf16 v[46:49], v[166:169], v[170:173], v[46:49]
	v_mfma_f32_16x16x32_bf16 v[38:41], v[166:169], v[174:177], v[38:41]
	v_mfma_f32_16x16x32_bf16 v[30:33], v[166:169], v[178:181], v[30:33]
	v_mfma_f32_16x16x32_bf16 v[22:25], v[166:169], v[200:203], v[22:25]
	s_add_u32 m0, s68, 0x400
	s_nop 0
	global_load_lds_dwordx4 v140, s[64:65]
	s_waitcnt lgkmcnt(0)
	s_nop 0
	v_mfma_f32_16x16x32_bf16 v[106:109], v[154:157], v[204:207], v[106:109]
	v_mfma_f32_16x16x32_bf16 v[98:101], v[154:157], v[208:211], v[98:101]
	v_mfma_f32_16x16x32_bf16 v[90:93], v[154:157], v[212:215], v[90:93]
	v_mfma_f32_16x16x32_bf16 v[82:85], v[154:157], v[216:219], v[82:85]
	v_mfma_f32_16x16x32_bf16 v[74:77], v[158:161], v[204:207], v[74:77]
	v_mfma_f32_16x16x32_bf16 v[66:69], v[158:161], v[208:211], v[66:69]
	v_mfma_f32_16x16x32_bf16 v[58:61], v[158:161], v[212:215], v[58:61]
	v_mfma_f32_16x16x32_bf16 v[50:53], v[158:161], v[216:219], v[50:53]
	v_mfma_f32_16x16x32_bf16 v[42:45], v[162:165], v[204:207], v[42:45]
	v_mfma_f32_16x16x32_bf16 v[34:37], v[162:165], v[208:211], v[34:37]
	v_mfma_f32_16x16x32_bf16 v[26:29], v[162:165], v[212:215], v[26:29]
	v_mfma_f32_16x16x32_bf16 v[18:21], v[162:165], v[216:219], v[18:21]
	v_mfma_f32_16x16x32_bf16 v[14:17], v[166:169], v[204:207], v[14:17]
	v_mfma_f32_16x16x32_bf16 v[10:13], v[166:169], v[208:211], v[10:13]
	v_mfma_f32_16x16x32_bf16 v[6:9], v[166:169], v[212:215], v[6:9]
	v_mfma_f32_16x16x32_bf16 v[2:5], v[166:169], v[216:219], v[2:5]
	s_add_i32 s10, s7, 0x6000
	s_cmpk_lg_u32 s7, 0xc000
	s_cselect_b32 s7, s10, 0
	s_addk_i32 s100, 0x400
	s_add_u32 s50, s50, s60
	s_addc_u32 s51, s51, 0
	s_cmpk_lg_i32 s100, 0x7800
	s_cbranch_scc1 .LBB0_246
	s_waitcnt vmcnt(6)
	s_barrier
	v_add_u32_e32 v0, s7, v150
	v_add_u32_e32 v140, s7, v149
	ds_read_b128 v[130:133], v0 offset:0
	ds_read_b128 v[136:139], v0 offset:0x400
	ds_read_b128 v[154:157], v0 offset:0x800
	ds_read_b128 v[158:161], v0 offset:0xc00
	ds_read_b128 v[162:165], v140 offset:0
	ds_read_b128 v[166:169], v140 offset:0x400
	ds_read_b128 v[170:173], v140 offset:0x800
	ds_read_b128 v[174:177], v140 offset:0xc00
	ds_read_b128 v[178:181], v140 offset:0x1000
	ds_read_b128 v[200:203], v140 offset:0x1400
	ds_read_b128 v[204:207], v140 offset:0x1800
	ds_read_b128 v[208:211], v140 offset:0x1c00
	s_lshl_b32 s49, s4, 8
	s_waitcnt lgkmcnt(4)
	s_nop 0
	v_mfma_f32_16x16x32_bf16 v[126:129], v[130:133], v[162:165], v[126:129]
	v_mfma_f32_16x16x32_bf16 v[118:121], v[130:133], v[170:173], v[118:121]
	v_mfma_f32_16x16x32_bf16 v[114:117], v[130:133], v[174:177], v[114:117]
	v_mfma_f32_16x16x32_bf16 v[110:113], v[136:139], v[162:165], v[110:113]
	v_mfma_f32_16x16x32_bf16 v[102:105], v[136:139], v[166:169], v[102:105]
	v_mfma_f32_16x16x32_bf16 v[94:97], v[136:139], v[170:173], v[94:97]
	v_mfma_f32_16x16x32_bf16 v[86:89], v[136:139], v[174:177], v[86:89]
	v_mfma_f32_16x16x32_bf16 v[70:73], v[154:157], v[166:169], v[70:73]
	v_mfma_f32_16x16x32_bf16 v[62:65], v[154:157], v[170:173], v[62:65]
	v_mfma_f32_16x16x32_bf16 v[54:57], v[154:157], v[174:177], v[54:57]
	v_mfma_f32_16x16x32_bf16 v[46:49], v[158:161], v[162:165], v[46:49]
	v_mfma_f32_16x16x32_bf16 v[38:41], v[158:161], v[166:169], v[38:41]
	v_mfma_f32_16x16x32_bf16 v[30:33], v[158:161], v[170:173], v[30:33]
	v_mfma_f32_16x16x32_bf16 v[22:25], v[158:161], v[174:177], v[22:25]
	v_mfma_f32_16x16x32_bf16 v[212:215], v[130:133], v[166:169], v[122:125]
	v_mfma_f32_16x16x32_bf16 v[216:219], v[154:157], v[162:165], v[78:81]
	s_waitcnt lgkmcnt(0)
	s_nop 0
	v_mfma_f32_16x16x32_bf16 v[174:177], v[136:139], v[178:181], v[74:77]
	v_mfma_f32_16x16x32_bf16 v[220:223], v[136:139], v[200:203], v[66:69]
	v_mfma_f32_16x16x32_bf16 v[224:227], v[136:139], v[204:207], v[58:61]
	v_mfma_f32_16x16x32_bf16 v[50:53], v[136:139], v[208:211], v[50:53]
	v_mfma_f32_16x16x32_bf16 v[136:139], v[154:157], v[178:181], v[42:45]
	v_mfma_f32_16x16x32_bf16 v[34:37], v[154:157], v[200:203], v[34:37]
	v_mfma_f32_16x16x32_bf16 v[6:9], v[158:161], v[204:207], v[6:9]
	v_mfma_f32_16x16x32_bf16 v[162:165], v[130:133], v[178:181], v[106:109]
	v_mfma_f32_16x16x32_bf16 v[166:169], v[130:133], v[200:203], v[98:101]
	v_mfma_f32_16x16x32_bf16 v[170:173], v[130:133], v[204:207], v[90:93]
	v_mfma_f32_16x16x32_bf16 v[130:133], v[130:133], v[208:211], v[82:85]
	v_mfma_f32_16x16x32_bf16 v[228:231], v[154:157], v[204:207], v[26:29]
	v_mfma_f32_16x16x32_bf16 v[154:157], v[154:157], v[208:211], v[18:21]
	v_mfma_f32_16x16x32_bf16 v[178:181], v[158:161], v[178:181], v[14:17]
	v_mfma_f32_16x16x32_bf16 v[200:203], v[158:161], v[200:203], v[10:13]
	v_mfma_f32_16x16x32_bf16 v[158:161], v[158:161], v[208:211], v[2:5]
	s_waitcnt vmcnt(0)
	s_barrier
	ds_read_b128 v[2:5], v151 offset:0
	ds_read_b128 v[14:17], v151 offset:0x400
	ds_read_b128 v[204:207], v151 offset:0x800
	ds_read_b128 v[208:211], v151 offset:0xc00
	ds_read_b128 v[10:13], v152 offset:0
	ds_read_b128 v[18:21], v152 offset:0x400
	ds_read_b128 v[26:29], v152 offset:0x800
	ds_read_b128 v[42:45], v152 offset:0xc00
	ds_read_b128 v[232:235], v152 offset:0x1000
	ds_read_b128 v[236:239], v152 offset:0x1400
	ds_read_b128 v[240:243], v152 offset:0x1800
	ds_read_b128 v[244:247], v152 offset:0x1c00
	s_nop 0
	s_waitcnt lgkmcnt(4)
	s_nop 0
	v_mfma_f32_16x16x32_bf16 v[122:125], v[2:5], v[10:13], v[126:129]
	v_mfma_f32_16x16x32_bf16 v[106:109], v[2:5], v[18:21], v[212:215]
	v_mfma_f32_16x16x32_bf16 v[90:93], v[2:5], v[26:29], v[118:121]
	v_mfma_f32_16x16x32_bf16 v[74:77], v[2:5], v[42:45], v[114:117]
	v_mfma_f32_16x16x32_bf16 v[126:129], v[14:17], v[10:13], v[110:113]
	v_mfma_f32_16x16x32_bf16 v[110:113], v[14:17], v[18:21], v[102:105]
	v_mfma_f32_16x16x32_bf16 v[94:97], v[14:17], v[26:29], v[94:97]
	v_mfma_f32_16x16x32_bf16 v[78:81], v[14:17], v[42:45], v[86:89]
	v_mfma_f32_16x16x32_bf16 v[114:117], v[204:207], v[10:13], v[216:219]
	v_mfma_f32_16x16x32_bf16 v[98:101], v[204:207], v[18:21], v[70:73]
	v_mfma_f32_16x16x32_bf16 v[82:85], v[204:207], v[26:29], v[62:65]
	v_mfma_f32_16x16x32_bf16 v[66:69], v[204:207], v[42:45], v[54:57]
	v_mfma_f32_16x16x32_bf16 v[118:121], v[208:211], v[10:13], v[46:49]
	v_mfma_f32_16x16x32_bf16 v[102:105], v[208:211], v[18:21], v[38:41]
	v_mfma_f32_16x16x32_bf16 v[86:89], v[208:211], v[26:29], v[30:33]
	v_mfma_f32_16x16x32_bf16 v[70:73], v[208:211], v[42:45], v[22:25]
	s_waitcnt lgkmcnt(0)
	s_nop 0
	v_mfma_f32_16x16x32_bf16 v[58:61], v[2:5], v[232:235], v[162:165]
	v_mfma_f32_16x16x32_bf16 v[42:45], v[2:5], v[236:239], v[166:169]
	v_mfma_f32_16x16x32_bf16 v[26:29], v[2:5], v[240:243], v[170:173]
	v_mfma_f32_16x16x32_bf16 v[10:13], v[2:5], v[244:247], v[130:133]
	v_mfma_f32_16x16x32_bf16 v[62:65], v[14:17], v[232:235], v[174:177]
	v_mfma_f32_16x16x32_bf16 v[46:49], v[14:17], v[236:239], v[220:223]
	v_mfma_f32_16x16x32_bf16 v[30:33], v[14:17], v[240:243], v[224:227]
	v_mfma_f32_16x16x32_bf16 v[14:17], v[14:17], v[244:247], v[50:53]
	v_mfma_f32_16x16x32_bf16 v[50:53], v[204:207], v[232:235], v[136:139]
	v_mfma_f32_16x16x32_bf16 v[34:37], v[204:207], v[236:239], v[34:37]
	v_mfma_f32_16x16x32_bf16 v[18:21], v[204:207], v[240:243], v[228:231]
	v_mfma_f32_16x16x32_bf16 v[2:5], v[204:207], v[244:247], v[154:157]
	v_mfma_f32_16x16x32_bf16 v[54:57], v[208:211], v[232:235], v[178:181]
	v_mfma_f32_16x16x32_bf16 v[38:41], v[208:211], v[236:239], v[200:203]
	v_mfma_f32_16x16x32_bf16 v[22:25], v[208:211], v[240:243], v[6:9]
	v_mfma_f32_16x16x32_bf16 v[6:9], v[208:211], v[244:247], v[158:161]
	v_mov_b32_e32 v136, v134
	s_mov_b64 s[50:51], -1
	s_and_b64 vcc, exec, s[22:23]
	s_barrier
	s_cbranch_vccz .LBB0_264
	s_and_b64 vcc, exec, s[0:1]
	s_cbranch_vccz .LBB0_250
	v_lshrrev_b32_e32 v0, 6, v136
	v_mul_lo_u32 v137, v0, s14
	v_and_b32_e32 v130, 15, v136
	v_and_or_b32 v0, v136, 48, v137
	s_movk_i32 s4, 0x90
	v_mad_u32_u24 v0, v130, s4, v0
	v_cvt_pk_bf16_f32 v130, v122, v123
	v_cvt_pk_bf16_f32 v131, v124, v125
	v_cvt_pk_bf16_f32 v132, v126, v127
	v_cvt_pk_bf16_f32 v133, v128, v129
	s_waitcnt vmcnt(0)
	ds_write_b128 v0, v[130:133]
	v_cvt_pk_bf16_f32 v130, v114, v115
	v_cvt_pk_bf16_f32 v131, v116, v117
	v_cvt_pk_bf16_f32 v132, v118, v119
	v_cvt_pk_bf16_f32 v133, v120, v121
	ds_write_b128 v0, v[130:133] offset:64
	v_cvt_pk_bf16_f32 v130, v106, v107
	v_cvt_pk_bf16_f32 v131, v108, v109
	v_cvt_pk_bf16_f32 v132, v110, v111
	v_cvt_pk_bf16_f32 v133, v112, v113
	ds_write_b128 v0, v[130:133] offset:2304
	v_cvt_pk_bf16_f32 v130, v98, v99
	v_cvt_pk_bf16_f32 v131, v100, v101
	v_cvt_pk_bf16_f32 v132, v102, v103
	v_cvt_pk_bf16_f32 v133, v104, v105
	ds_write_b128 v0, v[130:133] offset:2368
	v_cvt_pk_bf16_f32 v130, v90, v91
	v_cvt_pk_bf16_f32 v131, v92, v93
	v_cvt_pk_bf16_f32 v132, v94, v95
	v_cvt_pk_bf16_f32 v133, v96, v97
	ds_write_b128 v0, v[130:133] offset:4608
	v_cvt_pk_bf16_f32 v130, v82, v83
	v_cvt_pk_bf16_f32 v131, v84, v85
	v_cvt_pk_bf16_f32 v132, v86, v87
	v_cvt_pk_bf16_f32 v133, v88, v89
	ds_write_b128 v0, v[130:133] offset:4672
	v_cvt_pk_bf16_f32 v130, v74, v75
	v_cvt_pk_bf16_f32 v131, v76, v77
	v_cvt_pk_bf16_f32 v132, v78, v79
	v_cvt_pk_bf16_f32 v133, v80, v81
	ds_write_b128 v0, v[130:133] offset:6912
	v_cvt_pk_bf16_f32 v130, v66, v67
	v_cvt_pk_bf16_f32 v131, v68, v69
	v_cvt_pk_bf16_f32 v132, v70, v71
	v_cvt_pk_bf16_f32 v133, v72, v73
	ds_write_b128 v0, v[130:133] offset:6976
	v_cvt_pk_bf16_f32 v130, v58, v59
	v_cvt_pk_bf16_f32 v131, v60, v61
	v_cvt_pk_bf16_f32 v132, v62, v63
	v_cvt_pk_bf16_f32 v133, v64, v65
	ds_write_b128 v0, v[130:133] offset:9216
	v_cvt_pk_bf16_f32 v130, v50, v51
	v_cvt_pk_bf16_f32 v131, v52, v53
	v_cvt_pk_bf16_f32 v132, v54, v55
	v_cvt_pk_bf16_f32 v133, v56, v57
	ds_write_b128 v0, v[130:133] offset:9280
	v_cvt_pk_bf16_f32 v130, v42, v43
	v_cvt_pk_bf16_f32 v131, v44, v45
	v_cvt_pk_bf16_f32 v132, v46, v47
	v_cvt_pk_bf16_f32 v133, v48, v49
	ds_write_b128 v0, v[130:133] offset:11520
	v_cvt_pk_bf16_f32 v130, v34, v35
	v_cvt_pk_bf16_f32 v131, v36, v37
	v_cvt_pk_bf16_f32 v132, v38, v39
	v_cvt_pk_bf16_f32 v133, v40, v41
	ds_write_b128 v0, v[130:133] offset:11584
	v_cvt_pk_bf16_f32 v130, v26, v27
	v_cvt_pk_bf16_f32 v131, v28, v29
	v_cvt_pk_bf16_f32 v132, v30, v31
	v_cvt_pk_bf16_f32 v133, v32, v33
	ds_write_b128 v0, v[130:133] offset:13824
	v_cvt_pk_bf16_f32 v130, v18, v19
	v_cvt_pk_bf16_f32 v131, v20, v21
	v_cvt_pk_bf16_f32 v132, v22, v23
	v_cvt_pk_bf16_f32 v133, v24, v25
	ds_write_b128 v0, v[130:133] offset:13888
	v_cvt_pk_bf16_f32 v130, v10, v11
	v_cvt_pk_bf16_f32 v131, v12, v13
	v_cvt_pk_bf16_f32 v132, v14, v15
	v_cvt_pk_bf16_f32 v133, v16, v17
	ds_write_b128 v0, v[130:133] offset:16128
	v_cvt_pk_bf16_f32 v130, v2, v3
	v_cvt_pk_bf16_f32 v131, v4, v5
	v_cvt_pk_bf16_f32 v132, v6, v7
	v_cvt_pk_bf16_f32 v133, v8, v9
	ds_write_b128 v0, v[130:133] offset:16192
	v_and_b32_e32 v0, 0xffffff80, v136
	v_add_u32_e32 v130, s48, v0
	v_ashrrev_i32_e32 v131, 31, v130
	v_lshlrev_b64 v[130:131], 11, v[130:131]
	v_lshl_add_u64 v[130:131], s[38:39], 0, v[130:131]
	v_and_b32_e32 v0, 64, v136
	v_lshl_add_u64 v[130:131], s[46:47], 1, v[130:131]
	v_lshlrev_b32_e32 v0, 1, v0
	v_lshl_add_u64 v[138:139], v[130:131], 0, v[0:1]
	v_lshlrev_b32_e32 v0, 4, v136
	v_and_b32_e32 v0, 0x70, v0
	v_bfe_u32 v140, v136, 3, 3
	v_or_b32_e32 v130, v137, v0
	s_waitcnt lgkmcnt(0)
	v_mad_u32_u24 v137, v140, s4, v130
	ds_read_b128 v[130:133], v137
	v_lshl_add_u64 v[138:139], v[138:139], 0, v[0:1]
	v_lshlrev_b32_e32 v0, 11, v140
	v_lshl_add_u64 v[140:141], v[138:139], 0, v[0:1]
	s_mov_b64 s[50:51], 0
	s_waitcnt lgkmcnt(0)
	global_store_dwordx4 v[140:141], v[130:133], off
	ds_read_b128 v[130:133], v137 offset:1152
	v_or_b32_e32 v140, 0x4000, v0
	v_mov_b32_e32 v141, v1
	v_lshl_add_u64 v[140:141], v[138:139], 0, v[140:141]
	s_waitcnt lgkmcnt(0)
	global_store_dwordx4 v[140:141], v[130:133], off
	ds_read_b128 v[130:133], v137 offset:2304
	v_or_b32_e32 v140, 0x8000, v0
	v_mov_b32_e32 v141, v1
	v_lshl_add_u64 v[140:141], v[138:139], 0, v[140:141]
	s_waitcnt lgkmcnt(0)
	global_store_dwordx4 v[140:141], v[130:133], off
	ds_read_b128 v[130:133], v137 offset:3456
	v_or_b32_e32 v140, 0xc000, v0
	v_mov_b32_e32 v141, v1
	v_lshl_add_u64 v[140:141], v[138:139], 0, v[140:141]
	s_waitcnt lgkmcnt(0)
	global_store_dwordx4 v[140:141], v[130:133], off
	ds_read_b128 v[130:133], v137 offset:4608
	v_or_b32_e32 v140, 0x10000, v0
	v_mov_b32_e32 v141, v1
	v_lshl_add_u64 v[140:141], v[138:139], 0, v[140:141]
	s_waitcnt lgkmcnt(0)
	global_store_dwordx4 v[140:141], v[130:133], off
	ds_read_b128 v[130:133], v137 offset:5760
	v_or_b32_e32 v140, 0x14000, v0
	v_mov_b32_e32 v141, v1
	v_lshl_add_u64 v[140:141], v[138:139], 0, v[140:141]
	s_waitcnt lgkmcnt(0)
	global_store_dwordx4 v[140:141], v[130:133], off
	ds_read_b128 v[130:133], v137 offset:6912
	v_or_b32_e32 v140, 0x18000, v0
	v_mov_b32_e32 v141, v1
	v_lshl_add_u64 v[140:141], v[138:139], 0, v[140:141]
	s_waitcnt lgkmcnt(0)
	global_store_dwordx4 v[140:141], v[130:133], off
	ds_read_b128 v[130:133], v137 offset:8064
	v_or_b32_e32 v140, 0x1c000, v0
	v_mov_b32_e32 v141, v1
	v_lshl_add_u64 v[140:141], v[138:139], 0, v[140:141]
	s_waitcnt lgkmcnt(0)
	global_store_dwordx4 v[140:141], v[130:133], off
	ds_read_b128 v[130:133], v137 offset:9216
	v_or_b32_e32 v140, 0x20000, v0
	v_mov_b32_e32 v141, v1
	v_lshl_add_u64 v[140:141], v[138:139], 0, v[140:141]
	s_waitcnt lgkmcnt(0)
	global_store_dwordx4 v[140:141], v[130:133], off
	ds_read_b128 v[130:133], v137 offset:10368
	v_or_b32_e32 v140, 0x24000, v0
	v_mov_b32_e32 v141, v1
	v_lshl_add_u64 v[140:141], v[138:139], 0, v[140:141]
	s_waitcnt lgkmcnt(0)
	global_store_dwordx4 v[140:141], v[130:133], off
	ds_read_b128 v[130:133], v137 offset:11520
	v_or_b32_e32 v140, 0x28000, v0
	v_mov_b32_e32 v141, v1
	v_lshl_add_u64 v[140:141], v[138:139], 0, v[140:141]
	s_waitcnt lgkmcnt(0)
	global_store_dwordx4 v[140:141], v[130:133], off
	ds_read_b128 v[130:133], v137 offset:12672
	v_or_b32_e32 v140, 0x2c000, v0
	v_mov_b32_e32 v141, v1
	v_lshl_add_u64 v[140:141], v[138:139], 0, v[140:141]
	s_waitcnt lgkmcnt(0)
	global_store_dwordx4 v[140:141], v[130:133], off
	ds_read_b128 v[130:133], v137 offset:13824
	v_or_b32_e32 v140, 0x30000, v0
	v_mov_b32_e32 v141, v1
	v_lshl_add_u64 v[140:141], v[138:139], 0, v[140:141]
	s_waitcnt lgkmcnt(0)
	global_store_dwordx4 v[140:141], v[130:133], off
	ds_read_b128 v[130:133], v137 offset:14976
	v_or_b32_e32 v140, 0x34000, v0
	v_mov_b32_e32 v141, v1
	v_lshl_add_u64 v[140:141], v[138:139], 0, v[140:141]
	s_waitcnt lgkmcnt(0)
	global_store_dwordx4 v[140:141], v[130:133], off
	ds_read_b128 v[130:133], v137 offset:16128
	v_or_b32_e32 v140, 0x38000, v0
	v_mov_b32_e32 v141, v1
	v_lshl_add_u64 v[140:141], v[138:139], 0, v[140:141]
	v_or_b32_e32 v0, 0x3c000, v0
	s_waitcnt lgkmcnt(0)
	global_store_dwordx4 v[140:141], v[130:133], off
	ds_read_b128 v[130:133], v137 offset:17280
	v_lshl_add_u64 v[138:139], v[138:139], 0, v[0:1]
	s_waitcnt lgkmcnt(0)
	global_store_dwordx4 v[138:139], v[130:133], off
	s_waitcnt lgkmcnt(0)
	s_barrier
